# attention: 6 of 16 bias-table blocks kept resident in free VGPRs across items (reloaded only when r-r0 changes); waits recounted
# speedup vs baseline: 1.0032x; 1.0032x over previous
; __device__ __forceinline__ void attn_phase(LAS unsigned char* lds, const bf16_t* QKV, const float* TBL  , bf16_t* O, int tid, int wave, int lane, int G) {
;     LAS unsigned char* vt = lds + wave * 9216;
;     const unsigned vt_addr = (unsigned)(uintptr_t)vt;
;     const int fr = lane & 15, fq = lane >> 4;
;     for (int it = (int)blockIdx.x * NWAV + wave; it < 65536; it += G * NWAV) {
;         const int qt = it & 3, h = (it >> 2) & 15, r = (it >> 6) & 127, b = it >> 13;
;         const int r0 = min(max(r - 4, 0), 120), kc0 = qt == 0 ? 0 : (qt == 1 ? 8 : (qt == 2 ? 24 : 32));
;         const int c = 16 * qt + fr;
;         const size_t tokq = (size_t)b * SEQL + r * 64 + c;
;         const float* tb = TBL + ((size_t)(((r - r0) * 16 + h) * 4 + qt) * 16) * 256 + lane * 4;
;         bf16x8 qf[2];
;         const bf16_t* qh = QKV + ((size_t)(b * 16 + h) * SEQL) * 64; const bf16_t* kh = qh + (size_t)MTOK * DM; const bf16_t* vh = kh + (size_t)MTOK * DM;
;         {
;             const bf16_t* qsrc = qh + (size_t)(r * 64 + 16 * qt + (lane >> 3)) * 64 + (lane & 7) * 8;
;             const u32x4 q0 = *(const u32x4*)qsrc, q1 = *(const u32x4*)(qsrc + (size_t)8 * 64);
;             *(LAS u32x4*)(vt + (lane >> 3) * 144 + (lane & 7) * 16) = q0; *(LAS u32x4*)(vt + ((lane >> 3) + 8) * 144 + (lane & 7) * 16) = q1;
;             qf[0] = *(const LAS bf16x8*)(vt + fr * 144 + 16 * fq); qf[1] = *(const LAS bf16x8*)(vt + fr * 144 + 64 + 16 * fq);
;             asm volatile("s_waitcnt lgkmcnt(0)" ::: "memory"); }
;         const int vkey = lane >> 3, vch = lane & 7;
;         const bf16_t* vsrc = vh + (size_t)(r0 * 64 + kc0 + vkey) * 64 + vch * 8;
;         u32x4 vr[4][2][4];
;         f32x4 s[8][2]; u32x4 kr[4][2][4];
;         const bf16_t* ksrc = kh + (size_t)(r0 * 64 + kc0 + vkey) * 64 + vch * 8;
; #pragma unroll
;         for (int i = 0; i < 8; ++i) { const bf16_t* src = ksrc + (size_t)i * 64 * 64;
; #pragma unroll
;             for (int j = 0; j < 4; ++j) kr[i >> 1][i & 1][j] = *(const u32x4*)(src + (size_t)j * 8 * 64); }
; #pragma unroll
;         for (int i = 0; i < 8; ++i)
; #pragma unroll
;             for (int t = 0; t < 2; ++t) s[i][t] = i < 4 ? *(const f32x4*)(tb + (i * 2 + t) * 256) : (f32x4){0.f, 0.f, 0.f, 0.f};
.LBB0_362:
.LBB0_363:
	s_cmp_ge_i32 s26, s86
	s_cselect_b64 s[0:1], -1, 0
	s_and_b64 s[8:9], s[0:1], s[8:9]
	s_andn2_b64 vcc, exec, s[8:9]
	s_cbranch_vccnz .LBB0_373
	s_mov_b64 s[8:9], s[82:83]
	v_mov_b32_e32 v2, v202
	v_readlane_b32 s11, v254, 41
	v_readfirstlane_b32 s10, v2
	s_ashr_i32 s10, s10, 6
	s_add_i32 s12, s10, s11
	s_cmp_gt_i32 s12, 0xffff
	s_cbranch_scc1 .LBB0_372
	s_load_dwordx4 s[44:47], s[8:9], 0xb0
	v_readlane_b32 s8, v255, 25
	v_and_b32_e32 v0, 63, v2
	v_readlane_b32 s9, v255, 26
	s_mul_i32 s11, s10, 0x2400
	s_waitcnt lgkmcnt(0)
	s_add_u32 s13, s46, 0x10000000
	s_addc_u32 s14, s47, 0
	s_add_u32 s8, s46, s8
	s_addc_u32 s9, s47, s9
	v_lshlrev_b32_e32 v0, 4, v0
	s_add_i32 s11, s11, 0
	v_lshl_add_u64 v[4:5], s[8:9], 0, v[0:1]
	s_mov_b64 s[8:9], 0x36804000
	v_and_b32_e32 v3, 15, v2
	v_lshl_add_u64 v[162:163], v[4:5], 0, s[8:9]
	v_bfe_u32 v165, v2, 3, 3
	v_mov_b32_e32 v5, s11
	s_movk_i32 s8, 0x90
	v_and_b32_e32 v4, 7, v2
	v_mad_u32_u24 v6, v165, s8, v5
	v_mad_u32_u24 v200, v3, s8, v5
	v_and_b32_e32 v201, 48, v2
	v_bfe_u32 v5, v2, 2, 4
	v_lshlrev_b32_e32 v8, 3, v2
	v_lshrrev_b32_e32 v2, 1, v2
	s_and_b32 s15, s10, 3
	v_lshlrev_b32_e32 v0, 3, v4
	v_lshlrev_b32_e32 v4, 4, v4
	v_mul_u32_u24_e32 v7, 0x90, v3
	v_add_u32_e32 v3, s11, v201
	v_mul_u32_u24_e32 v5, 0x90, v5
	v_and_b32_e32 v8, 24, v8
	v_and_b32_e32 v2, 24, v2
	s_cmp_eq_u32 s15, 2
	v_add3_u32 v208, v5, v8, s11
	s_cselect_b32 s16, 24, 32
	v_lshl_or_b32 v164, s15, 4, v165
	v_lshlrev_b32_e32 v166, 1, v0
	v_add_u32_e32 v209, v6, v4
	v_add_u32_e32 v210, v3, v7
	v_add_u32_e32 v211, v200, v2
	s_mov_b32 s100, -1
	s_branch .LBB0_367
.LBB0_366:
	s_bfe_u32 s10, s12, 0x70006
	v_sub_u32_e64 v0, s10, 4 clamp
	s_bfe_u32 s17, s12, 0x40002
	v_readfirstlane_b32 s9, v0
	s_min_u32 s20, s9, 0x78
	s_lshl_b32 s18, s10, 6
	s_sub_i32 s10, s10, s20
	s_mov_b32 s101, s10
	s_ashr_i32 s8, s12, 13
	s_lshl_b32 s10, s10, 6
	s_lshl_b32 s11, s17, 2
	s_or_b32 s10, s10, s11
	s_lshl_b32 s21, s8, 4
	s_or_b32 s10, s10, s15
	s_or_b32 s30, s21, s17
	s_ashr_i32 s11, s10, 31
	s_ashr_i32 s31, s30, 31
	s_ashr_i32 s9, s8, 31
	s_lshl_b64 s[10:11], s[10:11], 14
	s_lshl_b64 s[30:31], s[30:31], 20
	s_add_u32 s30, s13, s30
	v_or_b32_e32 v0, s18, v164
	s_addc_u32 s31, s14, s31
	v_lshlrev_b32_e32 v0, 7, v0
	v_lshl_add_u64 v[2:3], s[30:31], 0, v[0:1]
	v_mov_b32_e32 v167, v1
	v_lshl_add_u64 v[6:7], v[2:3], 0, v[166:167]
	global_load_dwordx4 v[2:5], v[6:7], off
	s_nop 0
	global_load_dwordx4 v[6:9], v[6:7], off offset:1024
	s_lshl_b32 s20, s20, 6
	s_or_b32 s19, s19, s20
	v_or_b32_e32 v0, s19, v165
	v_lshlrev_b32_e32 v0, 7, v0
	v_lshl_add_u64 v[10:11], s[30:31], 0, v[0:1]
	v_lshl_add_u64 v[18:19], v[10:11], 0, v[166:167]
	s_brev_b32 s19, 16
	v_add_co_u32_e32 v20, vcc, s19, v18
	s_mov_b32 s19, 0x8002000
	s_nop 0
	v_addc_co_u32_e32 v21, vcc, 0, v19, vcc
	v_add_co_u32_e32 v40, vcc, s19, v18
	s_mov_b32 s19, 0x8004000
	s_nop 0
	v_addc_co_u32_e32 v41, vcc, 0, v19, vcc
	v_add_co_u32_e32 v56, vcc, s19, v18
	s_mov_b32 s19, 0x8006000
	s_nop 0
	v_addc_co_u32_e32 v57, vcc, 0, v19, vcc
	v_add_co_u32_e32 v72, vcc, s19, v18
	s_mov_b32 s19, 0x8008000
	s_nop 0
	v_addc_co_u32_e32 v73, vcc, 0, v19, vcc
	v_add_co_u32_e32 v88, vcc, s19, v18
	s_mov_b32 s19, 0x800a000
	s_nop 0
	v_addc_co_u32_e32 v89, vcc, 0, v19, vcc
	v_add_co_u32_e32 v104, vcc, s19, v18
	s_mov_b32 s19, 0x800c000
	s_nop 0
	v_addc_co_u32_e32 v105, vcc, 0, v19, vcc
	v_add_u32_e32 v0, v200, v201
	s_mov_b64 s[30:31], 0x8000000
	v_add_co_u32_e32 v120, vcc, s19, v18
	v_lshl_add_u64 v[24:25], v[18:19], 0, s[30:31]
	s_nop 0
	v_addc_co_u32_e32 v121, vcc, 0, v19, vcc
	s_mov_b32 s19, 0x800e000
	v_add_co_u32_e32 v128, vcc, s19, v18
	v_lshl_add_u64 v[192:193], v[162:163], 0, s[10:11]
	s_nop 0
	v_addc_co_u32_e32 v129, vcc, 0, v19, vcc
	s_movk_i32 s10, 0x1000
	v_add_co_u32_e32 v140, vcc, s10, v192
	s_movk_i32 s10, 0x2000
	s_nop 0
	v_addc_co_u32_e32 v141, vcc, 0, v193, vcc
	v_add_co_u32_e32 v194, vcc, s10, v192
	s_lshl_b64 s[8:9], s[8:9], 13
	s_nop 0
	v_addc_co_u32_e32 v195, vcc, 0, v193, vcc
	s_or_b32 s8, s8, s18
	global_load_dwordx4 v[10:13], v[24:25], off offset:1024
	global_load_dwordx4 v[14:17], v[24:25], off offset:2048
	s_nop 0
	global_load_dwordx4 v[20:23], v[20:21], off
	s_nop 0
	global_load_dwordx4 v[24:27], v[24:25], off offset:3072
	s_nop 0
	global_load_dwordx4 v[28:31], v[40:41], off
	global_load_dwordx4 v[32:35], v[40:41], off offset:1024
	global_load_dwordx4 v[36:39], v[40:41], off offset:2048
	s_nop 0
	global_load_dwordx4 v[40:43], v[40:41], off offset:3072
	s_nop 0
	global_load_dwordx4 v[44:47], v[56:57], off
	global_load_dwordx4 v[48:51], v[56:57], off offset:1024
	global_load_dwordx4 v[52:55], v[56:57], off offset:2048
	s_nop 0
	global_load_dwordx4 v[56:59], v[56:57], off offset:3072
	s_nop 0
	global_load_dwordx4 v[60:63], v[72:73], off
	global_load_dwordx4 v[64:67], v[72:73], off offset:1024
	global_load_dwordx4 v[68:71], v[72:73], off offset:2048
	s_nop 0
	global_load_dwordx4 v[72:75], v[72:73], off offset:3072
	s_nop 0
	global_load_dwordx4 v[76:79], v[88:89], off
	global_load_dwordx4 v[80:83], v[88:89], off offset:1024
	global_load_dwordx4 v[84:87], v[88:89], off offset:2048
	s_nop 0
	global_load_dwordx4 v[88:91], v[88:89], off offset:3072
	s_nop 0
	global_load_dwordx4 v[92:95], v[104:105], off
	global_load_dwordx4 v[96:99], v[104:105], off offset:1024
	global_load_dwordx4 v[100:103], v[104:105], off offset:2048
	s_nop 0
	global_load_dwordx4 v[104:107], v[104:105], off offset:3072
	s_nop 0
	global_load_dwordx4 v[108:111], v[120:121], off
	global_load_dwordx4 v[112:115], v[120:121], off offset:1024
	global_load_dwordx4 v[116:119], v[120:121], off offset:2048
	s_nop 0
	global_load_dwordx4 v[120:123], v[120:121], off offset:3072
	s_nop 0
	global_load_dwordx4 v[124:127], v[128:129], off
	global_load_dwordx4 v[158:161], v[128:129], off offset:1024
	global_load_dwordx4 v[168:171], v[128:129], off offset:2048
	global_load_dwordx4 v[172:175], v[128:129], off offset:3072
	s_nop 0
	s_cmp_eq_u32 s101, s100
	s_cbranch_scc1 .Lattn_tb_res
	global_load_dwordx4 v[222:225], v[192:193], off
	global_load_dwordx4 v[226:229], v[192:193], off offset:1024
	global_load_dwordx4 v[230:233], v[192:193], off offset:2048
	global_load_dwordx4 v[238:241], v[192:193], off offset:3072
	global_load_dwordx4 v[242:245], v[140:141], off offset:1024
	global_load_dwordx4 v[246:249], v[140:141], off offset:2048
	s_mov_b32 s100, s101
; __device__ __forceinline__ void attn_phase(LAS unsigned char* lds, const bf16_t* QKV, const float* TBL  , bf16_t* O, int tid, int wave, int lane, int G) {
;     ...
; #pragma unroll
;         for (int i = 0; i < 8; ++i) { const bf16_t* src = ksrc + (size_t)i * 64 * 64;
; #pragma unroll
;             for (int j = 0; j < 4; ++j) kr[i >> 1][i & 1][j] = *(const u32x4*)(src + (size_t)j * 8 * 64); }
; #pragma unroll
;         for (int i = 0; i < 8; ++i)
; #pragma unroll
;             for (int t = 0; t < 2; ++t) s[i][t] = i < 4 ? *(const f32x4*)(tb + (i * 2 + t) * 256) : (f32x4){0.f, 0.f, 0.f, 0.f};
;         __builtin_amdgcn_sched_barrier(0);
;         f32x4 tb2[4][2];
; #pragma unroll
;         for (int ip = 0; ip < 4; ++ip) {
; #pragma unroll
;             for (int rr = 0; rr < 2; ++rr) { LAS unsigned char* dst = vt + rr * 4608 + vkey * 144 + vch * 16;
; #pragma unroll
;                 for (int j = 0; j < 4; ++j) *(LAS u32x4*)(dst + j * 8 * 144) = kr[ip][rr][j]; }
;             if (ip == 1) {
; #pragma unroll
;                 for (int i = 0; i < 4; ++i)
; #pragma unroll
;                     for (int t = 0; t < 2; ++t) tb2[i][t] = *(const f32x4*)(tb + ((i + 4) * 2 + t) * 256); }
; #pragma unroll
;             for (int rr = 0; rr < 2; ++rr)
; #pragma unroll
;                 for (int t = 0; t < 2; ++t) { const LAS unsigned char* kp = vt + rr * 4608 + (16 * t + fr) * 144 + 16 * fq;
;                     const bf16x8 k0 = *(const LAS bf16x8*)kp, k1 = *(const LAS bf16x8*)(kp + 64);
;                     s[2 * ip + rr][t] = __builtin_amdgcn_mfma_f32_16x16x32_bf16(k0, qf[0], s[2 * ip + rr][t], 0, 0, 0); s[2 * ip + rr][t] = __builtin_amdgcn_mfma_f32_16x16x32_bf16(k1, qf[1], s[2 * ip + rr][t], 0, 0, 0); }
;             asm volatile("s_waitcnt lgkmcnt(0)" ::: "memory");
;         }
; #pragma unroll
;         for (int i = 0; i < 4; ++i)
; #pragma unroll
;             for (int t = 0; t < 2; ++t) s[i + 4][t] = s[i + 4][t] + tb2[i][t];
.Lattn_tb_res:
	global_load_dwordx4 v[184:187], v[194:195], off offset:-4096
	global_load_dwordx4 v[188:191], v[140:141], off offset:3072
	s_waitcnt vmcnt(34)
	ds_write_b128 v209, v[2:5]
	ds_write_b128 v209, v[6:9] offset:1152
	ds_read_b128 v[6:9], v0
	ds_read_b128 v[2:5], v0 offset:64
	s_waitcnt lgkmcnt(0)
	s_waitcnt vmcnt(31)
	ds_write_b128 v209, v[20:23]
	ds_write_b128 v209, v[10:13] offset:1152
	ds_write_b128 v209, v[14:17] offset:2304
	s_waitcnt vmcnt(30)
	ds_write_b128 v209, v[24:27] offset:3456
	s_waitcnt vmcnt(29)
	ds_write_b128 v209, v[28:31] offset:4608
	s_waitcnt vmcnt(28)
	ds_write_b128 v209, v[32:35] offset:5760
	s_waitcnt vmcnt(27)
	ds_write_b128 v209, v[36:39] offset:6912
	s_waitcnt vmcnt(26)
	ds_write_b128 v209, v[40:43] offset:8064
	ds_read_b128 v[10:13], v210
	ds_read_b128 v[14:17], v210 offset:64
	ds_read_b128 v[20:23], v210 offset:2304
	ds_read_b128 v[24:27], v210 offset:2368
	s_movk_i32 s10, 0x3000
	s_waitcnt vmcnt(2) lgkmcnt(3)
	v_mfma_f32_16x16x32_bf16 v[10:13], v[10:13], v[6:9], v[222:225]
	s_waitcnt lgkmcnt(2)
	v_mfma_f32_16x16x32_bf16 v[154:157], v[14:17], v[2:5], v[10:13]
	ds_read_b128 v[14:17], v210 offset:4672
	s_nop 4
	ds_read_b128 v[10:13], v210 offset:4608
	s_waitcnt vmcnt(2) lgkmcnt(3)
	v_mfma_f32_16x16x32_bf16 v[20:23], v[20:23], v[6:9], v[226:229]
	s_waitcnt lgkmcnt(2)
	v_mfma_f32_16x16x32_bf16 v[150:153], v[24:27], v[2:5], v[20:23]
	s_nop 5
	ds_read_b128 v[20:23], v210 offset:6912
	ds_read_b128 v[24:27], v210 offset:6976
	s_waitcnt lgkmcnt(0)
	ds_write_b128 v209, v[44:47]
	ds_write_b128 v209, v[48:51] offset:1152
	ds_write_b128 v209, v[52:55] offset:2304
	s_waitcnt vmcnt(2) lgkmcnt(5)
	v_mfma_f32_16x16x32_bf16 v[10:13], v[10:13], v[6:9], v[230:233]
	ds_write_b128 v209, v[56:59] offset:3456
	ds_write_b128 v209, v[60:63] offset:4608
	ds_write_b128 v209, v[64:67] offset:5760
	ds_write_b128 v209, v[68:71] offset:6912
	ds_write_b128 v209, v[72:75] offset:8064
	v_add_co_u32_e32 v48, vcc, s10, v192
	v_mfma_f32_16x16x32_bf16 v[142:145], v[14:17], v[2:5], v[10:13]
	ds_read_b128 v[14:17], v210
	v_addc_co_u32_e32 v49, vcc, 0, v193, vcc
	s_waitcnt vmcnt(2) lgkmcnt(10)
	v_mfma_f32_16x16x32_bf16 v[10:13], v[20:23], v[6:9], v[238:241]
	s_mov_b64 s[10:11], 0x10000000
	s_waitcnt lgkmcnt(9)
	v_mfma_f32_16x16x32_bf16 v[146:149], v[24:27], v[2:5], v[10:13]
	s_nop 4
	ds_read_b128 v[10:13], v210 offset:64
	s_waitcnt vmcnt(1) lgkmcnt(1)
	v_mfma_f32_16x16x32_bf16 v[14:17], v[14:17], v[6:9], v[184:187]
	ds_read_b128 v[20:23], v210 offset:2304
	ds_read_b128 v[24:27], v210 offset:2368
	s_waitcnt lgkmcnt(2)
	v_mfma_f32_16x16x32_bf16 v[138:141], v[10:13], v[2:5], v[14:17]
	global_load_dwordx4 v[10:13], v[194:195], off
	s_nop 2
	global_load_dwordx4 v[14:17], v[194:195], off offset:1024
	ds_read_b128 v[28:31], v210 offset:4608
	global_load_dwordx4 v[32:35], v[194:195], off offset:2048
	global_load_dwordx4 v[36:39], v[194:195], off offset:3072
	s_waitcnt lgkmcnt(2)
	v_mfma_f32_16x16x32_bf16 v[20:23], v[20:23], v[6:9], v[242:245]
	ds_read_b128 v[40:43], v210 offset:4672
	s_waitcnt lgkmcnt(2)
	v_mfma_f32_16x16x32_bf16 v[134:137], v[24:27], v[2:5], v[20:23]
	s_waitcnt lgkmcnt(1)
	v_mfma_f32_16x16x32_bf16 v[20:23], v[28:31], v[6:9], v[246:249]
	global_load_dwordx4 v[24:27], v[48:49], off
	global_load_dwordx4 v[28:31], v[48:49], off offset:1024
	global_load_dwordx4 v[44:47], v[48:49], off offset:2048
	s_nop 0
	global_load_dwordx4 v[48:51], v[48:49], off offset:3072
	s_waitcnt lgkmcnt(0)
	v_mfma_f32_16x16x32_bf16 v[130:133], v[40:43], v[2:5], v[20:23]
	s_nop 2
	ds_read_b128 v[20:23], v210 offset:6912
	ds_read_b128 v[40:43], v210 offset:6976
	s_waitcnt lgkmcnt(0)
	ds_write_b128 v209, v[76:79]
	ds_write_b128 v209, v[80:83] offset:1152
	ds_write_b128 v209, v[84:87] offset:2304
	ds_write_b128 v209, v[88:91] offset:3456
	ds_write_b128 v209, v[92:95] offset:4608
	ds_write_b128 v209, v[96:99] offset:5760
	ds_write_b128 v209, v[100:103] offset:6912
	ds_write_b128 v209, v[104:107] offset:8064
	ds_read_b128 v[52:55], v210
	ds_read_b128 v[56:59], v210 offset:64
	s_waitcnt lgkmcnt(1)
	v_mfma_f32_16x16x32_bf16 v[52:55], v[52:55], v[6:9], 0
	ds_read_b128 v[60:63], v210 offset:2304
	ds_read_b128 v[64:67], v210 offset:4608
	s_waitcnt lgkmcnt(2)
	v_mfma_f32_16x16x32_bf16 v[52:55], v[56:59], v[2:5], v[52:55]
	ds_read_b128 v[56:59], v210 offset:2368
	s_waitcnt lgkmcnt(2)
	v_mfma_f32_16x16x32_bf16 v[60:63], v[60:63], v[6:9], 0
	s_waitcnt vmcnt(7)
	s_nop 3
	v_pk_add_f32 v[196:197], v[12:13], v[54:55]
	s_waitcnt lgkmcnt(0)
	v_mfma_f32_16x16x32_bf16 v[56:59], v[56:59], v[2:5], v[60:63]
	v_add_f32_e64 v198, v10, v52
	v_add_f32_e64 v199, v11, v53
	s_nop 0
	ds_read_b128 v[60:63], v210 offset:4672
	v_mfma_f32_16x16x32_bf16 v[64:67], v[64:67], v[6:9], 0
	ds_read_b128 v[68:71], v210 offset:6912
	ds_read_b128 v[72:75], v210 offset:6976
	s_waitcnt lgkmcnt(0)
	ds_write_b128 v209, v[108:111]
	ds_write_b128 v209, v[112:115] offset:1152
	ds_write_b128 v209, v[116:119] offset:2304
	ds_write_b128 v209, v[120:123] offset:3456
	ds_write_b128 v209, v[124:127] offset:4608
	ds_write_b128 v209, v[158:161] offset:5760
	ds_write_b128 v209, v[168:171] offset:6912
	ds_write_b128 v209, v[172:175] offset:8064
	s_waitcnt lgkmcnt(10)
	v_mfma_f32_16x16x32_bf16 v[60:63], v[60:63], v[2:5], v[64:67]
	ds_read_b128 v[76:79], v210 offset:2304
	s_waitcnt vmcnt(6)
	v_pk_add_f32 v[192:193], v[16:17], v[58:59]
	v_pk_add_f32 v[194:195], v[14:15], v[56:57]
	s_waitcnt lgkmcnt(10)
	v_mfma_f32_16x16x32_bf16 v[64:67], v[68:71], v[6:9], 0
	ds_read_b128 v[68:71], v210
	s_waitcnt lgkmcnt(10)
	v_mfma_f32_16x16x32_bf16 v[64:67], v[72:75], v[2:5], v[64:67]
	ds_read_b128 v[72:75], v210 offset:64
	s_waitcnt lgkmcnt(1)
; __device__ __forceinline__ void attn_phase(LAS unsigned char* lds, const bf16_t* QKV, const float* TBL  , bf16_t* O, int tid, int wave, int lane, int G) {
;     ...
; #pragma unroll
;             for (int rr = 0; rr < 2; ++rr)
; #pragma unroll
;                 for (int t = 0; t < 2; ++t) { const LAS unsigned char* kp = vt + rr * 4608 + (16 * t + fr) * 144 + 16 * fq;
;                     const bf16x8 k0 = *(const LAS bf16x8*)kp, k1 = *(const LAS bf16x8*)(kp + 64);
;                     s[2 * ip + rr][t] = __builtin_amdgcn_mfma_f32_16x16x32_bf16(k0, qf[0], s[2 * ip + rr][t], 0, 0, 0); s[2 * ip + rr][t] = __builtin_amdgcn_mfma_f32_16x16x32_bf16(k1, qf[1], s[2 * ip + rr][t], 0, 0, 0); }
;             asm volatile("s_waitcnt lgkmcnt(0)" ::: "memory");
;         }
; #pragma unroll
;         for (int i = 0; i < 4; ++i)
; #pragma unroll
;             for (int t = 0; t < 2; ++t) s[i + 4][t] = s[i + 4][t] + tb2[i][t];
;         __builtin_amdgcn_sched_barrier(0);
; #pragma unroll
;         for (int i = 0; i < 8; ++i) { const bf16_t* src = vsrc + (size_t)i * 64 * 64;
; #pragma unroll
;             for (int j = 0; j < 4; ++j) vr[i >> 1][i & 1][j] = *(const u32x4*)(src + (size_t)j * 8 * 64); }
;         __builtin_amdgcn_sched_barrier(0);
;         float mx = -1e30f;
; #pragma unroll
;         for (int i = 0; i < 8; ++i)
; #pragma unroll
;             for (int t = 0; t < 2; ++t) mx = fmaxf(fmaxf(mx, fmaxf(s[i][t][0], s[i][t][1])), fmaxf(s[i][t][2], s[i][t][3]));
;         mx = fmaxf(mx, __shfl_xor(mx, 16)); mx = fmaxf(mx, __shfl_xor(mx, 32));
	v_mfma_f32_16x16x32_bf16 v[68:71], v[68:71], v[6:9], 0
	s_waitcnt vmcnt(4)
	s_nop 3
	v_pk_add_f32 v[184:185], v[38:39], v[66:67]
	s_waitcnt lgkmcnt(0)
	v_mfma_f32_16x16x32_bf16 v[68:71], v[72:75], v[2:5], v[68:71]
	ds_read_b128 v[72:75], v210 offset:2368
	ds_read_b128 v[80:83], v210 offset:4608
	ds_read_b128 v[84:87], v210 offset:4672
	ds_read_b128 v[88:91], v210 offset:6912
	ds_read_b128 v[92:95], v210 offset:6976
	s_waitcnt lgkmcnt(0)
	v_mfma_f32_16x16x32_bf16 v[20:23], v[20:23], v[6:9], v[188:191]
	v_add_f32_e64 v186, v36, v64
	v_add_f32_e64 v187, v37, v65
	s_waitcnt vmcnt(3)
	v_pk_add_f32 v[180:181], v[26:27], v[70:71]
	v_pk_add_f32 v[182:183], v[24:25], v[68:69]
	v_mfma_f32_16x16x32_bf16 v[76:79], v[76:79], v[6:9], 0
	v_add_f32_e64 v188, v34, v62
	v_add_f32_e64 v189, v35, v63
	v_pk_add_f32 v[190:191], v[32:33], v[60:61]
	s_waitcnt lgkmcnt(3)
	v_mfma_f32_16x16x32_bf16 v[10:13], v[80:83], v[6:9], 0
	s_waitcnt lgkmcnt(1)
	v_mfma_f32_16x16x32_bf16 v[6:9], v[88:91], v[6:9], 0
	v_mfma_f32_16x16x32_bf16 v[72:75], v[72:75], v[2:5], v[76:79]
	v_mfma_f32_16x16x32_bf16 v[10:13], v[84:87], v[2:5], v[10:13]
	s_waitcnt lgkmcnt(0)
	v_mfma_f32_16x16x32_bf16 v[6:9], v[92:95], v[2:5], v[6:9]
	s_waitcnt vmcnt(2)
	s_nop 3
	v_pk_add_f32 v[176:177], v[30:31], v[74:75]
	v_pk_add_f32 v[178:179], v[28:29], v[72:73]
	s_waitcnt vmcnt(1)
	v_pk_add_f32 v[172:173], v[46:47], v[12:13]
	v_pk_add_f32 v[174:175], v[44:45], v[10:11]
	v_mfma_f32_16x16x32_bf16 v[158:161], v[40:43], v[2:5], v[20:23]
	s_waitcnt vmcnt(0)
	v_pk_add_f32 v[168:169], v[50:51], v[8:9]
	v_pk_add_f32 v[170:171], v[48:49], v[6:7]
	v_lshl_add_u64 v[2:3], v[18:19], 0, s[10:11]
	v_add_co_u32_e32 v4, vcc, s73, v18
	s_mov_b32 s10, 0x10002000
	s_nop 0
	v_addc_co_u32_e32 v5, vcc, 0, v19, vcc
	global_load_dwordx4 v[98:101], v[2:3], off offset:1024
	global_load_dwordx4 v[102:105], v[2:3], off offset:2048
	global_load_dwordx4 v[110:113], v[4:5], off
	global_load_dwordx4 v[106:109], v[2:3], off offset:3072
	v_add_co_u32_e32 v2, vcc, s10, v18
	s_mov_b32 s10, 0x10004000
	s_nop 0
	v_addc_co_u32_e32 v3, vcc, 0, v19, vcc
	global_load_dwordx4 v[114:117], v[2:3], off
	global_load_dwordx4 v[118:121], v[2:3], off offset:1024
	global_load_dwordx4 v[122:125], v[2:3], off offset:2048
	global_load_dwordx4 v[126:129], v[2:3], off offset:3072
	v_add_co_u32_e32 v2, vcc, s10, v18
	s_mov_b32 s10, 0x10006000
	s_nop 0
	v_addc_co_u32_e32 v3, vcc, 0, v19, vcc
	global_load_dwordx4 v[66:69], v[2:3], off
	global_load_dwordx4 v[70:73], v[2:3], off offset:1024
	global_load_dwordx4 v[74:77], v[2:3], off offset:2048
	global_load_dwordx4 v[78:81], v[2:3], off offset:3072
	v_add_co_u32_e32 v2, vcc, s10, v18
	s_mov_b32 s10, 0x10008000
	s_nop 0
	v_addc_co_u32_e32 v3, vcc, 0, v19, vcc
	global_load_dwordx4 v[82:85], v[2:3], off
	global_load_dwordx4 v[86:89], v[2:3], off offset:1024
	global_load_dwordx4 v[90:93], v[2:3], off offset:2048
	global_load_dwordx4 v[94:97], v[2:3], off offset:3072
	v_add_co_u32_e32 v2, vcc, s10, v18
	s_mov_b32 s10, 0x1000a000
	s_nop 0
	v_addc_co_u32_e32 v3, vcc, 0, v19, vcc
	global_load_dwordx4 v[34:37], v[2:3], off
	global_load_dwordx4 v[38:41], v[2:3], off offset:1024
	global_load_dwordx4 v[42:45], v[2:3], off offset:2048
	global_load_dwordx4 v[46:49], v[2:3], off offset:3072
	v_add_co_u32_e32 v2, vcc, s10, v18
	s_mov_b32 s10, 0x1000c000
	s_nop 0
	v_addc_co_u32_e32 v3, vcc, 0, v19, vcc
	v_add_co_u32_e32 v14, vcc, s10, v18
	s_mov_b32 s10, 0x1000e000
	s_nop 0
	v_addc_co_u32_e32 v15, vcc, 0, v19, vcc
	v_add_co_u32_e32 v30, vcc, s10, v18
	global_load_dwordx4 v[50:53], v[2:3], off
	global_load_dwordx4 v[54:57], v[2:3], off offset:1024
	global_load_dwordx4 v[58:61], v[2:3], off offset:2048
	global_load_dwordx4 v[62:65], v[2:3], off offset:3072
	v_addc_co_u32_e32 v31, vcc, 0, v19, vcc
	global_load_dwordx4 v[2:5], v[14:15], off
	global_load_dwordx4 v[6:9], v[14:15], off offset:1024
	global_load_dwordx4 v[10:13], v[14:15], off offset:2048
	s_nop 0
	global_load_dwordx4 v[14:17], v[14:15], off offset:3072
	s_nop 0
	global_load_dwordx4 v[18:21], v[30:31], off
	global_load_dwordx4 v[22:25], v[30:31], off offset:1024
	global_load_dwordx4 v[26:29], v[30:31], off offset:2048
	s_nop 0
	global_load_dwordx4 v[30:33], v[30:31], off offset:3072
	v_max_f32_e32 v0, v155, v155
	v_max_f32_e32 v204, v154, v154
	v_max_f32_e32 v0, v204, v0
	v_max_f32_e32 v204, v157, v157
	v_max_f32_e32 v205, v156, v156
	v_max_f32_e32 v204, v205, v204
	s_mov_b32 s10, 0xf149f2ca
	v_max3_f32 v0, v0, s10, v204
	v_max_f32_e32 v204, v151, v151
	v_max_f32_e32 v205, v150, v150
	v_max_f32_e32 v204, v205, v204
	v_max_f32_e32 v205, v153, v153
	v_max_f32_e32 v212, v152, v152
	v_max_f32_e32 v205, v212, v205
	v_max3_f32 v0, v0, v204, v205
	v_max_f32_e32 v204, v143, v143
	v_max_f32_e32 v205, v142, v142
	v_max_f32_e32 v204, v205, v204
	v_max_f32_e32 v205, v145, v145
	v_max_f32_e32 v212, v144, v144
	v_max_f32_e32 v205, v212, v205
	v_max3_f32 v0, v0, v204, v205
	v_max_f32_e32 v204, v147, v147
	v_max_f32_e32 v205, v146, v146
	v_max_f32_e32 v204, v205, v204
	v_max_f32_e32 v205, v149, v149
	v_max_f32_e32 v212, v148, v148
	v_max_f32_e32 v205, v212, v205
	v_max3_f32 v0, v0, v204, v205
	v_max_f32_e32 v204, v139, v139
	v_max_f32_e32 v205, v138, v138
	v_max_f32_e32 v204, v205, v204
	v_max_f32_e32 v205, v141, v141
	v_max_f32_e32 v212, v140, v140
	v_max_f32_e32 v205, v212, v205
	v_max3_f32 v0, v0, v204, v205
	v_max_f32_e32 v204, v135, v135
	v_max_f32_e32 v205, v134, v134
	v_max_f32_e32 v204, v205, v204
	v_max_f32_e32 v205, v137, v137
	v_max_f32_e32 v212, v136, v136
	v_max_f32_e32 v205, v212, v205
	v_max3_f32 v0, v0, v204, v205
	v_max_f32_e32 v204, v131, v131
	v_max_f32_e32 v205, v130, v130
	v_max_f32_e32 v204, v205, v204
	v_max_f32_e32 v205, v133, v133
	v_max_f32_e32 v212, v132, v132
	v_max_f32_e32 v205, v212, v205
	v_max3_f32 v0, v0, v204, v205
	v_max_f32_e32 v204, v159, v159
	v_max_f32_e32 v205, v158, v158
	v_max_f32_e32 v204, v205, v204
	v_max_f32_e32 v205, v161, v161
	v_max_f32_e32 v212, v160, v160
	v_max_f32_e32 v205, v212, v205
	v_max3_f32 v0, v0, v204, v205
	v_max_f32_e32 v204, v198, v199
	v_max_f32_e32 v205, v196, v197
	v_max3_f32 v0, v0, v204, v205
	v_max_f32_e32 v204, v194, v195
	v_max_f32_e32 v205, v192, v193
	v_max3_f32 v0, v0, v204, v205
	v_max_f32_e32 v204, v190, v191
	v_max_f32_e32 v205, v188, v189
	v_max3_f32 v0, v0, v204, v205
	v_max_f32_e32 v204, v186, v187
	v_max_f32_e32 v205, v184, v185
	v_max3_f32 v0, v0, v204, v205
	v_max_f32_e32 v204, v182, v183
	v_max_f32_e32 v205, v180, v181
	v_max3_f32 v0, v0, v204, v205
	v_max_f32_e32 v204, v178, v179
	v_max_f32_e32 v205, v176, v177
	v_max3_f32 v0, v0, v204, v205
	v_max_f32_e32 v204, v174, v175
	v_max_f32_e32 v205, v172, v173
	v_max3_f32 v0, v0, v204, v205
	v_max_f32_e32 v204, v170, v171
	v_max_f32_e32 v205, v168, v169
	v_max3_f32 v204, v0, v204, v205
	v_and_b32_e32 v205, 64, v237
	v_xor_b32_e32 v0, 16, v237
	v_add_u32_e32 v205, 64, v205
	v_cmp_lt_i32_e32 vcc, v0, v205
	s_waitcnt vmcnt(29)
; __device__ __forceinline__ u32x4 pack8(const f32x4 a, const f32x4 b) { u32x4 w; w.x = cvt_pk_bf16(a[0], a[1]); w.y = cvt_pk_bf16(a[2], a[3]); w.z = cvt_pk_bf16(b[0], b[1]); w.w = cvt_pk_bf16(b[2], b[3]); return w; }
; __device__ __forceinline__ void attn_phase(LAS unsigned char* lds, const bf16_t* QKV, const float* TBL  , bf16_t* O, int tid, int wave, int lane, int G) {
;     ...
;         mx = fmaxf(mx, __shfl_xor(mx, 16)); mx = fmaxf(mx, __shfl_xor(mx, 32));
;         float sum = 0.f;
; #pragma unroll
;         for (int i = 0; i < 8; ++i)
; #pragma unroll
;             for (int t = 0; t < 2; ++t)
; #pragma unroll
;                 for (int e = 0; e < 4; ++e) { const float pe = __builtin_amdgcn_exp2f(s[i][t][e] - mx); s[i][t][e] = pe; sum += pe; }
;         sum += __shfl_xor(sum, 16); sum += __shfl_xor(sum, 32);
;         f32x4 o[4];
; #pragma unroll
;         for (int dt = 0; dt < 4; ++dt) o[dt] = (f32x4){0.f, 0.f, 0.f, 0.f};
;         const unsigned ad = vt_addr + (unsigned)((4 * fq + (fr >> 2)) * 144 + 8 * (fr & 3));
; #pragma unroll
;         for (int ip = 0; ip < 4; ++ip) {
; #pragma unroll
;             for (int rr = 0; rr < 2; ++rr) { LAS unsigned char* dst = vt + rr * 4608 + vkey * 144 + vch * 16;
; #pragma unroll
;                 for (int j = 0; j < 4; ++j) *(LAS u32x4*)(dst + j * 8 * 144) = vr[ip][rr][j]; }
;             union { u32x4 w; bf16x8 v; } pf0, pf1; pf0.w = pack8(s[2 * ip][0], s[2 * ip][1]); pf1.w = pack8(s[2 * ip + 1][0], s[2 * ip + 1][1]);
;             s16x4 ta0, ta1, ta2, ta3, tb0, tb1, tb2, tb3, ua0, ua1, ua2, ua3, ub0, ub1, ub2, ub3;
;             asm volatile("ds_read_b64_tr_b16 %0, %16\n\tds_read_b64_tr_b16 %1, %16 offset:32\n\tds_read_b64_tr_b16 %2, %16 offset:64\n\tds_read_b64_tr_b16 %3, %16 offset:96\n\t"
;                          "ds_read_b64_tr_b16 %4, %16 offset:2304\n\tds_read_b64_tr_b16 %5, %16 offset:2336\n\tds_read_b64_tr_b16 %6, %16 offset:2368\n\tds_read_b64_tr_b16 %7, %16 offset:2400\n\t"
;                          "ds_read_b64_tr_b16 %8, %16 offset:4608\n\tds_read_b64_tr_b16 %9, %16 offset:4640\n\tds_read_b64_tr_b16 %10, %16 offset:4672\n\tds_read_b64_tr_b16 %11, %16 offset:4704\n\t"
;                          "ds_read_b64_tr_b16 %12, %16 offset:6912\n\tds_read_b64_tr_b16 %13, %16 offset:6944\n\tds_read_b64_tr_b16 %14, %16 offset:6976\n\tds_read_b64_tr_b16 %15, %16 offset:7008\n\ts_waitcnt lgkmcnt(0)"
	ds_write_b128 v209, v[110:113]
	ds_write_b128 v209, v[98:101] offset:1152
	ds_write_b128 v209, v[102:105] offset:2304
	s_waitcnt vmcnt(28)
	ds_write_b128 v209, v[106:109] offset:3456
	s_waitcnt vmcnt(27)
	ds_write_b128 v209, v[114:117] offset:4608
	s_waitcnt vmcnt(26)
	ds_write_b128 v209, v[118:121] offset:5760
	s_waitcnt vmcnt(25)
	ds_write_b128 v209, v[122:125] offset:6912
	s_waitcnt vmcnt(24)
	ds_write_b128 v209, v[126:129] offset:8064
	v_cndmask_b32_e32 v0, v237, v0, vcc
	v_lshlrev_b32_e32 v0, 2, v0
	ds_bpermute_b32 v212, v0, v204
	s_lshl_b32 s26, s17, 7
	s_add_i32 s12, s12, s38
	s_cmp_lt_i32 s12, 0x10000
	s_waitcnt lgkmcnt(0)
	v_max_f32_e32 v212, v212, v212
	v_max_f32_e32 v204, v204, v212
	v_xor_b32_e32 v212, 32, v237
	v_cmp_lt_i32_e32 vcc, v212, v205
	s_nop 1
	v_cndmask_b32_e32 v205, v237, v212, vcc
	v_lshlrev_b32_e32 v212, 2, v205
	ds_bpermute_b32 v205, v212, v204
	s_waitcnt lgkmcnt(0)
	v_max_f32_e32 v205, v205, v205
	v_max_f32_e32 v213, v204, v205
	v_sub_f32_e32 v154, v154, v213
	v_exp_f32_e32 v154, v154
	v_sub_f32_e32 v155, v155, v213
	v_exp_f32_e32 v155, v155
	v_sub_f32_e32 v156, v156, v213
	v_exp_f32_e32 v156, v156
	v_sub_f32_e32 v157, v157, v213
	v_exp_f32_e32 v157, v157
	v_sub_f32_e32 v150, v150, v213
	v_add_f32_e32 v204, 0, v154
	v_exp_f32_e32 v150, v150
	v_sub_f32_e32 v151, v151, v213
	v_add_f32_e32 v204, v155, v204
	v_exp_f32_e32 v151, v151
	v_sub_f32_e32 v152, v152, v213
	v_add_f32_e32 v204, v156, v204
	v_exp_f32_e32 v152, v152
	v_sub_f32_e32 v153, v153, v213
	v_add_f32_e32 v204, v157, v204
	v_exp_f32_e32 v153, v153
	v_sub_f32_e32 v142, v142, v213
	v_add_f32_e32 v204, v150, v204
	v_exp_f32_e32 v142, v142
	v_sub_f32_e32 v143, v143, v213
	v_add_f32_e32 v204, v151, v204
	v_exp_f32_e32 v143, v143
	v_sub_f32_e32 v144, v144, v213
	v_add_f32_e32 v204, v152, v204
	v_exp_f32_e32 v144, v144
	v_sub_f32_e32 v145, v145, v213
	v_add_f32_e32 v204, v153, v204
	v_exp_f32_e32 v145, v145
	v_sub_f32_e32 v146, v146, v213
	v_add_f32_e32 v204, v142, v204
	v_exp_f32_e32 v146, v146
	v_sub_f32_e32 v147, v147, v213
	v_add_f32_e32 v204, v143, v204
	v_exp_f32_e32 v147, v147
	v_sub_f32_e32 v148, v148, v213
	v_add_f32_e32 v204, v144, v204
	v_exp_f32_e32 v148, v148
	v_sub_f32_e32 v149, v149, v213
	v_add_f32_e32 v204, v145, v204
	v_exp_f32_e32 v149, v149
	v_sub_f32_e32 v138, v138, v213
	v_add_f32_e32 v204, v146, v204
	v_exp_f32_e32 v138, v138
	v_sub_f32_e32 v139, v139, v213
	v_add_f32_e32 v204, v147, v204
	v_exp_f32_e32 v139, v139
	v_sub_f32_e32 v140, v140, v213
	v_add_f32_e32 v204, v148, v204
	v_exp_f32_e32 v140, v140
	v_sub_f32_e32 v141, v141, v213
	v_add_f32_e32 v204, v149, v204
	v_exp_f32_e32 v141, v141
	v_sub_f32_e32 v134, v134, v213
	v_add_f32_e32 v204, v138, v204
	v_exp_f32_e32 v205, v134
	v_sub_f32_e32 v135, v135, v213
	v_add_f32_e32 v134, v139, v204
	v_exp_f32_e32 v204, v135
	v_sub_f32_e32 v135, v136, v213
	v_add_f32_e32 v134, v140, v134
	v_exp_f32_e32 v214, v135
	v_sub_f32_e32 v135, v137, v213
	v_add_f32_e32 v134, v141, v134
	v_exp_f32_e32 v215, v135
	v_sub_f32_e32 v130, v130, v213
	v_add_f32_e32 v134, v205, v134
	v_exp_f32_e32 v216, v130
	v_sub_f32_e32 v131, v131, v213
	v_add_f32_e32 v130, v204, v134
	v_exp_f32_e32 v217, v131
	v_sub_f32_e32 v131, v132, v213
	v_add_f32_e32 v130, v214, v130
	v_exp_f32_e32 v218, v131
	v_sub_f32_e32 v131, v133, v213
	v_add_f32_e32 v130, v215, v130
	v_exp_f32_e32 v219, v131
	v_sub_f32_e32 v131, v158, v213
	v_add_f32_e32 v130, v216, v130
	v_exp_f32_e32 v158, v131
	v_sub_f32_e32 v131, v159, v213
	v_add_f32_e32 v130, v217, v130
	v_exp_f32_e32 v159, v131
	v_sub_f32_e32 v131, v160, v213
	v_add_f32_e32 v130, v218, v130
	v_exp_f32_e32 v160, v131
	v_sub_f32_e32 v131, v161, v213
	v_add_f32_e32 v130, v219, v130
	v_exp_f32_e32 v161, v131
	v_sub_f32_e32 v131, v198, v213
	v_add_f32_e32 v130, v158, v130
	v_exp_f32_e32 v198, v131
	v_sub_f32_e32 v131, v199, v213
	v_add_f32_e32 v130, v159, v130
	v_exp_f32_e32 v199, v131
	v_sub_f32_e32 v131, v196, v213
	v_add_f32_e32 v130, v160, v130
	v_exp_f32_e32 v196, v131
	v_sub_f32_e32 v131, v197, v213
	v_add_f32_e32 v130, v161, v130
	v_exp_f32_e32 v197, v131
	v_sub_f32_e32 v131, v194, v213
	v_add_f32_e32 v130, v198, v130
	v_exp_f32_e32 v194, v131
	v_add_f32_e32 v130, v199, v130
	v_add_f32_e32 v130, v196, v130
	v_add_f32_e32 v130, v197, v130
	v_add_f32_e32 v220, v194, v130
	v_sub_f32_e32 v130, v195, v213
	v_exp_f32_e32 v195, v130
	v_sub_f32_e32 v130, v192, v213
	v_exp_f32_e32 v192, v130
	v_sub_f32_e32 v130, v193, v213
	v_exp_f32_e32 v193, v130
	v_cvt_pk_bf16_f32 v98, v154, v155
	v_cvt_pk_bf16_f32 v99, v156, v157
	v_cvt_pk_bf16_f32 v100, v150, v151
	v_cvt_pk_bf16_f32 v101, v152, v153
	v_cvt_pk_bf16_f32 v102, v142, v143
	v_cvt_pk_bf16_f32 v103, v144, v145
	v_cvt_pk_bf16_f32 v104, v146, v147
	v_cvt_pk_bf16_f32 v105, v148, v149
	ds_read_b64_tr_b16 v[134:135], v208
	ds_read_b64_tr_b16 v[130:131], v208 offset:32
	ds_read_b64_tr_b16 v[126:127], v208 offset:64
	ds_read_b64_tr_b16 v[122:123], v208 offset:96
	ds_read_b64_tr_b16 v[136:137], v208 offset:2304
	ds_read_b64_tr_b16 v[132:133], v208 offset:2336
	ds_read_b64_tr_b16 v[128:129], v208 offset:2368
	ds_read_b64_tr_b16 v[124:125], v208 offset:2400
	ds_read_b64_tr_b16 v[118:119], v208 offset:4608
	ds_read_b64_tr_b16 v[114:115], v208 offset:4640
	ds_read_b64_tr_b16 v[110:111], v208 offset:4672
	ds_read_b64_tr_b16 v[106:107], v208 offset:4704
	ds_read_b64_tr_b16 v[120:121], v208 offset:6912
	ds_read_b64_tr_b16 v[116:117], v208 offset:6944
	ds_read_b64_tr_b16 v[112:113], v208 offset:6976
	ds_read_b64_tr_b16 v[108:109], v208 offset:7008
	s_waitcnt lgkmcnt(0)
	v_sub_f32_e32 v143, v190, v213
	v_mfma_f32_16x16x32_bf16 v[134:137], v[134:137], v[98:101], 0
	s_waitcnt vmcnt(23)
; __device__ __forceinline__ void attn_phase(LAS unsigned char* lds, const bf16_t* QKV, const float* TBL  , bf16_t* O, int tid, int wave, int lane, int G) {
;     ...
;         for (int ip = 0; ip < 4; ++ip) {
; #pragma unroll
;             for (int rr = 0; rr < 2; ++rr) { LAS unsigned char* dst = vt + rr * 4608 + vkey * 144 + vch * 16;
; #pragma unroll
;                 for (int j = 0; j < 4; ++j) *(LAS u32x4*)(dst + j * 8 * 144) = vr[ip][rr][j]; }
;             union { u32x4 w; bf16x8 v; } pf0, pf1; pf0.w = pack8(s[2 * ip][0], s[2 * ip][1]); pf1.w = pack8(s[2 * ip + 1][0], s[2 * ip + 1][1]);
;             s16x4 ta0, ta1, ta2, ta3, tb0, tb1, tb2, tb3, ua0, ua1, ua2, ua3, ub0, ub1, ub2, ub3;
;             asm volatile("ds_read_b64_tr_b16 %0, %16\n\tds_read_b64_tr_b16 %1, %16 offset:32\n\tds_read_b64_tr_b16 %2, %16 offset:64\n\tds_read_b64_tr_b16 %3, %16 offset:96\n\t"
;                          "ds_read_b64_tr_b16 %4, %16 offset:2304\n\tds_read_b64_tr_b16 %5, %16 offset:2336\n\tds_read_b64_tr_b16 %6, %16 offset:2368\n\tds_read_b64_tr_b16 %7, %16 offset:2400\n\t"
;                          "ds_read_b64_tr_b16 %8, %16 offset:4608\n\tds_read_b64_tr_b16 %9, %16 offset:4640\n\tds_read_b64_tr_b16 %10, %16 offset:4672\n\tds_read_b64_tr_b16 %11, %16 offset:4704\n\t"
;                          "ds_read_b64_tr_b16 %12, %16 offset:6912\n\tds_read_b64_tr_b16 %13, %16 offset:6944\n\tds_read_b64_tr_b16 %14, %16 offset:6976\n\tds_read_b64_tr_b16 %15, %16 offset:7008\n\ts_waitcnt lgkmcnt(0)"
;                          : "=&v"(ta0), "=&v"(ta1), "=&v"(ta2), "=&v"(ta3), "=&v"(tb0), "=&v"(tb1), "=&v"(tb2), "=&v"(tb3), "=&v"(ua0), "=&v"(ua1), "=&v"(ua2), "=&v"(ua3), "=&v"(ub0), "=&v"(ub1), "=&v"(ub2), "=&v"(ub3) : "v"(ad) : "memory");
;             bf16x8 vf;
;             vf = (bf16x8){ta0[0], ta0[1], ta0[2], ta0[3], tb0[0], tb0[1], tb0[2], tb0[3]}; o[0] = __builtin_amdgcn_mfma_f32_16x16x32_bf16(vf, pf0.v, o[0], 0, 0, 0);
;             vf = (bf16x8){ta1[0], ta1[1], ta1[2], ta1[3], tb1[0], tb1[1], tb1[2], tb1[3]}; o[1] = __builtin_amdgcn_mfma_f32_16x16x32_bf16(vf, pf0.v, o[1], 0, 0, 0);
;             vf = (bf16x8){ta2[0], ta2[1], ta2[2], ta2[3], tb2[0], tb2[1], tb2[2], tb2[3]}; o[2] = __builtin_amdgcn_mfma_f32_16x16x32_bf16(vf, pf0.v, o[2], 0, 0, 0);
	ds_write_b128 v209, v[66:69]
	s_waitcnt vmcnt(22)
	ds_write_b128 v209, v[70:73] offset:1152
	s_waitcnt vmcnt(21)
	ds_write_b128 v209, v[74:77] offset:2304
	s_waitcnt vmcnt(20)
	ds_write_b128 v209, v[78:81] offset:3456
	s_waitcnt vmcnt(19)
	ds_write_b128 v209, v[82:85] offset:4608
	s_waitcnt vmcnt(18)
	ds_write_b128 v209, v[86:89] offset:5760
	s_waitcnt vmcnt(17)
	ds_write_b128 v209, v[90:93] offset:6912
	s_waitcnt vmcnt(16)
	ds_write_b128 v209, v[94:97] offset:8064
	v_cvt_pk_bf16_f32 v66, v138, v139
	v_cvt_pk_bf16_f32 v67, v140, v141
	v_mfma_f32_16x16x32_bf16 v[126:129], v[126:129], v[98:101], 0
	v_cvt_pk_bf16_f32 v68, v205, v204
	v_cvt_pk_bf16_f32 v69, v214, v215
	v_cvt_pk_bf16_f32 v70, v216, v217
	v_mfma_f32_16x16x32_bf16 v[130:133], v[130:133], v[98:101], 0
	v_cvt_pk_bf16_f32 v71, v218, v219
	v_cvt_pk_bf16_f32 v72, v158, v159
	v_cvt_pk_bf16_f32 v73, v160, v161
	v_mfma_f32_16x16x32_bf16 v[98:101], v[122:125], v[98:101], 0
	v_exp_f32_e32 v143, v143
	v_sub_f32_e32 v144, v191, v213
	v_add_f32_e32 v142, v195, v220
	v_mfma_f32_16x16x32_bf16 v[118:121], v[118:121], v[102:105], v[134:137]
	v_exp_f32_e32 v144, v144
	v_sub_f32_e32 v145, v188, v213
	v_add_f32_e32 v142, v192, v142
	v_mfma_f32_16x16x32_bf16 v[110:113], v[110:113], v[102:105], v[126:129]
	v_exp_f32_e32 v145, v145
	v_sub_f32_e32 v123, v189, v213
	v_add_f32_e32 v142, v193, v142
	v_mfma_f32_16x16x32_bf16 v[114:117], v[114:117], v[102:105], v[130:133]
	v_exp_f32_e32 v123, v123
	v_sub_f32_e32 v124, v186, v213
	v_add_f32_e32 v122, v143, v142
	v_mfma_f32_16x16x32_bf16 v[98:101], v[106:109], v[102:105], v[98:101]
	ds_read_b64_tr_b16 v[106:107], v208
	ds_read_b64_tr_b16 v[102:103], v208 offset:32
	ds_read_b64_tr_b16 v[94:95], v208 offset:64
	ds_read_b64_tr_b16 v[90:91], v208 offset:96
	ds_read_b64_tr_b16 v[108:109], v208 offset:2304
	ds_read_b64_tr_b16 v[104:105], v208 offset:2336
	ds_read_b64_tr_b16 v[96:97], v208 offset:2368
	ds_read_b64_tr_b16 v[92:93], v208 offset:2400
	ds_read_b64_tr_b16 v[86:87], v208 offset:4608
	ds_read_b64_tr_b16 v[82:83], v208 offset:4640
	ds_read_b64_tr_b16 v[78:79], v208 offset:4672
	ds_read_b64_tr_b16 v[74:75], v208 offset:4704
	ds_read_b64_tr_b16 v[88:89], v208 offset:6912
	ds_read_b64_tr_b16 v[84:85], v208 offset:6944
	ds_read_b64_tr_b16 v[80:81], v208 offset:6976
	ds_read_b64_tr_b16 v[76:77], v208 offset:7008
	s_waitcnt lgkmcnt(0)
	v_exp_f32_e32 v124, v124
	v_sub_f32_e32 v125, v187, v213
	v_mfma_f32_16x16x32_bf16 v[106:109], v[106:109], v[66:69], v[118:121]
	v_add_f32_e32 v122, v144, v122
	v_exp_f32_e32 v125, v125
	v_add_f32_e32 v122, v145, v122
	v_mfma_f32_16x16x32_bf16 v[94:97], v[94:97], v[66:69], v[110:113]
	v_sub_f32_e32 v118, v184, v213
	v_exp_f32_e32 v118, v118
	v_sub_f32_e32 v119, v185, v213
	v_mfma_f32_16x16x32_bf16 v[102:105], v[102:105], v[66:69], v[114:117]
	v_add_f32_e32 v122, v123, v122
	s_waitcnt vmcnt(15)
	ds_write_b128 v209, v[34:37]
	s_waitcnt vmcnt(14)
	ds_write_b128 v209, v[38:41] offset:1152
	s_waitcnt vmcnt(13)
	ds_write_b128 v209, v[42:45] offset:2304
	s_waitcnt vmcnt(12)
	ds_write_b128 v209, v[46:49] offset:3456
	s_waitcnt vmcnt(11)
	ds_write_b128 v209, v[50:53] offset:4608
	s_waitcnt vmcnt(10)
	ds_write_b128 v209, v[54:57] offset:5760
	s_waitcnt vmcnt(9)
	ds_write_b128 v209, v[58:61] offset:6912
	s_waitcnt vmcnt(8)
	ds_write_b128 v209, v[62:65] offset:8064
	v_exp_f32_e32 v114, v119
	v_mfma_f32_16x16x32_bf16 v[66:69], v[90:93], v[66:69], v[98:101]
	v_sub_f32_e32 v115, v182, v213
	v_cvt_pk_bf16_f32 v34, v198, v199
	v_cvt_pk_bf16_f32 v35, v196, v197
	v_mfma_f32_16x16x32_bf16 v[86:89], v[86:89], v[70:73], v[106:109]
	v_cvt_pk_bf16_f32 v36, v194, v195
	v_cvt_pk_bf16_f32 v37, v192, v193
	v_cvt_pk_bf16_f32 v38, v143, v144
	v_mfma_f32_16x16x32_bf16 v[78:81], v[78:81], v[70:73], v[94:97]
	v_cvt_pk_bf16_f32 v39, v145, v123
	v_cvt_pk_bf16_f32 v40, v124, v125
	v_cvt_pk_bf16_f32 v41, v118, v114
	v_mfma_f32_16x16x32_bf16 v[82:85], v[82:85], v[70:73], v[102:105]
	v_add_f32_e32 v122, v124, v122
	v_exp_f32_e32 v115, v115
	v_sub_f32_e32 v90, v183, v213
	v_mfma_f32_16x16x32_bf16 v[66:69], v[74:77], v[70:73], v[66:69]
	ds_read_b64_tr_b16 v[74:75], v208
	ds_read_b64_tr_b16 v[70:71], v208 offset:32
	ds_read_b64_tr_b16 v[62:63], v208 offset:64
	ds_read_b64_tr_b16 v[58:59], v208 offset:96
	ds_read_b64_tr_b16 v[76:77], v208 offset:2304
	ds_read_b64_tr_b16 v[72:73], v208 offset:2336
	ds_read_b64_tr_b16 v[64:65], v208 offset:2368
	ds_read_b64_tr_b16 v[60:61], v208 offset:2400
	ds_read_b64_tr_b16 v[54:55], v208 offset:4608
	ds_read_b64_tr_b16 v[50:51], v208 offset:4640
	ds_read_b64_tr_b16 v[46:47], v208 offset:4672
	ds_read_b64_tr_b16 v[42:43], v208 offset:4704
	ds_read_b64_tr_b16 v[56:57], v208 offset:6912
	ds_read_b64_tr_b16 v[52:53], v208 offset:6944
	ds_read_b64_tr_b16 v[48:49], v208 offset:6976
	ds_read_b64_tr_b16 v[44:45], v208 offset:7008
	s_waitcnt lgkmcnt(0)
; __device__ __forceinline__ void attn_phase(LAS unsigned char* lds, const bf16_t* QKV, const float* TBL  , bf16_t* O, int tid, int wave, int lane, int G) {
;     ...
;         for (int ip = 0; ip < 4; ++ip) {
; #pragma unroll
;             for (int rr = 0; rr < 2; ++rr) { LAS unsigned char* dst = vt + rr * 4608 + vkey * 144 + vch * 16;
; #pragma unroll
;                 for (int j = 0; j < 4; ++j) *(LAS u32x4*)(dst + j * 8 * 144) = vr[ip][rr][j]; }
;             union { u32x4 w; bf16x8 v; } pf0, pf1; pf0.w = pack8(s[2 * ip][0], s[2 * ip][1]); pf1.w = pack8(s[2 * ip + 1][0], s[2 * ip + 1][1]);
;             s16x4 ta0, ta1, ta2, ta3, tb0, tb1, tb2, tb3, ua0, ua1, ua2, ua3, ub0, ub1, ub2, ub3;
;             asm volatile("ds_read_b64_tr_b16 %0, %16\n\tds_read_b64_tr_b16 %1, %16 offset:32\n\tds_read_b64_tr_b16 %2, %16 offset:64\n\tds_read_b64_tr_b16 %3, %16 offset:96\n\t"
;                          "ds_read_b64_tr_b16 %4, %16 offset:2304\n\tds_read_b64_tr_b16 %5, %16 offset:2336\n\tds_read_b64_tr_b16 %6, %16 offset:2368\n\tds_read_b64_tr_b16 %7, %16 offset:2400\n\t"
;                          "ds_read_b64_tr_b16 %8, %16 offset:4608\n\tds_read_b64_tr_b16 %9, %16 offset:4640\n\tds_read_b64_tr_b16 %10, %16 offset:4672\n\tds_read_b64_tr_b16 %11, %16 offset:4704\n\t"
;                          "ds_read_b64_tr_b16 %12, %16 offset:6912\n\tds_read_b64_tr_b16 %13, %16 offset:6944\n\tds_read_b64_tr_b16 %14, %16 offset:6976\n\tds_read_b64_tr_b16 %15, %16 offset:7008\n\ts_waitcnt lgkmcnt(0)"
;                          : "=&v"(ta0), "=&v"(ta1), "=&v"(ta2), "=&v"(ta3), "=&v"(tb0), "=&v"(tb1), "=&v"(tb2), "=&v"(tb3), "=&v"(ua0), "=&v"(ua1), "=&v"(ua2), "=&v"(ua3), "=&v"(ub0), "=&v"(ub1), "=&v"(ub2), "=&v"(ub3) : "v"(ad) : "memory");
;             bf16x8 vf;
;             vf = (bf16x8){ta0[0], ta0[1], ta0[2], ta0[3], tb0[0], tb0[1], tb0[2], tb0[3]}; o[0] = __builtin_amdgcn_mfma_f32_16x16x32_bf16(vf, pf0.v, o[0], 0, 0, 0);
;             vf = (bf16x8){ta1[0], ta1[1], ta1[2], ta1[3], tb1[0], tb1[1], tb1[2], tb1[3]}; o[1] = __builtin_amdgcn_mfma_f32_16x16x32_bf16(vf, pf0.v, o[1], 0, 0, 0);
;             vf = (bf16x8){ta2[0], ta2[1], ta2[2], ta2[3], tb2[0], tb2[1], tb2[2], tb2[3]}; o[2] = __builtin_amdgcn_mfma_f32_16x16x32_bf16(vf, pf0.v, o[2], 0, 0, 0);
	v_add_f32_e32 v122, v125, v122
	v_exp_f32_e32 v90, v90
	v_mfma_f32_16x16x32_bf16 v[74:77], v[74:77], v[34:37], v[86:89]
	v_sub_f32_e32 v91, v180, v213
	v_add_f32_e32 v110, v118, v122
	v_exp_f32_e32 v91, v91
	v_sub_f32_e32 v92, v181, v213
	v_mfma_f32_16x16x32_bf16 v[62:65], v[62:65], v[34:37], v[78:81]
	v_add_f32_e32 v110, v114, v110
	v_exp_f32_e32 v92, v92
	v_sub_f32_e32 v94, v178, v213
	v_mfma_f32_16x16x32_bf16 v[70:73], v[70:73], v[34:37], v[82:85]
	v_add_f32_e32 v110, v115, v110
	v_exp_f32_e32 v94, v94
	v_sub_f32_e32 v95, v179, v213
	v_mfma_f32_16x16x32_bf16 v[34:37], v[58:61], v[34:37], v[66:69]
	v_add_f32_e32 v93, v90, v110
	v_exp_f32_e32 v86, v95
	v_sub_f32_e32 v87, v176, v213
	v_mfma_f32_16x16x32_bf16 v[54:57], v[54:57], v[38:41], v[74:77]
	v_add_f32_e32 v93, v91, v93
	v_exp_f32_e32 v87, v87
	v_sub_f32_e32 v82, v177, v213
	v_sub_f32_e32 v83, v174, v213
	v_sub_f32_e32 v79, v175, v213
	v_sub_f32_e32 v58, v172, v213
	v_sub_f32_e32 v59, v173, v213
	v_sub_f32_e32 v60, v170, v213
	v_sub_f32_e32 v61, v171, v213
	v_sub_f32_e32 v66, v168, v213
	v_mfma_f32_16x16x32_bf16 v[46:49], v[46:49], v[38:41], v[62:65]
	v_add_f32_e32 v93, v92, v93
	v_exp_f32_e32 v82, v82
	v_exp_f32_e32 v78, v83
	v_sub_f32_e32 v63, v169, v213
	v_exp_f32_e32 v79, v79
	v_exp_f32_e32 v58, v58
	v_exp_f32_e32 v59, v59
	v_exp_f32_e32 v60, v60
	v_mfma_f32_16x16x32_bf16 v[50:53], v[50:53], v[38:41], v[70:73]
	v_exp_f32_e32 v61, v61
	v_exp_f32_e32 v62, v66
	v_exp_f32_e32 v63, v63
	v_mfma_f32_16x16x32_bf16 v[34:37], v[42:45], v[38:41], v[34:37]
	s_waitcnt vmcnt(7)
	ds_write_b128 v209, v[2:5]
	s_waitcnt vmcnt(6)
	ds_write_b128 v209, v[6:9] offset:1152
	s_waitcnt vmcnt(5)
	ds_write_b128 v209, v[10:13] offset:2304
	s_waitcnt vmcnt(4)
	ds_write_b128 v209, v[14:17] offset:3456
	s_waitcnt vmcnt(3)
	ds_write_b128 v209, v[18:21] offset:4608
	s_waitcnt vmcnt(2)
	ds_write_b128 v209, v[22:25] offset:5760
	s_waitcnt vmcnt(1)
	ds_write_b128 v209, v[26:29] offset:6912
	s_waitcnt vmcnt(0)
	ds_write_b128 v209, v[30:33] offset:8064
	v_cvt_pk_bf16_f32 v2, v115, v90
	v_cvt_pk_bf16_f32 v3, v91, v92
	v_cvt_pk_bf16_f32 v4, v94, v86
	v_cvt_pk_bf16_f32 v5, v87, v82
	v_cvt_pk_bf16_f32 v6, v78, v79
	v_cvt_pk_bf16_f32 v7, v58, v59
	v_cvt_pk_bf16_f32 v8, v60, v61
	v_cvt_pk_bf16_f32 v9, v62, v63
	ds_read_b64_tr_b16 v[42:43], v208
	ds_read_b64_tr_b16 v[38:39], v208 offset:32
	ds_read_b64_tr_b16 v[30:31], v208 offset:64
	ds_read_b64_tr_b16 v[26:27], v208 offset:96
	ds_read_b64_tr_b16 v[44:45], v208 offset:2304
	ds_read_b64_tr_b16 v[40:41], v208 offset:2336
	ds_read_b64_tr_b16 v[32:33], v208 offset:2368
	ds_read_b64_tr_b16 v[28:29], v208 offset:2400
	ds_read_b64_tr_b16 v[22:23], v208 offset:4608
	ds_read_b64_tr_b16 v[18:19], v208 offset:4640
	ds_read_b64_tr_b16 v[14:15], v208 offset:4672
	ds_read_b64_tr_b16 v[10:11], v208 offset:4704
	ds_read_b64_tr_b16 v[24:25], v208 offset:6912
	ds_read_b64_tr_b16 v[20:21], v208 offset:6944
	ds_read_b64_tr_b16 v[16:17], v208 offset:6976
	ds_read_b64_tr_b16 v[12:13], v208 offset:7008
	s_waitcnt lgkmcnt(0)
	s_nop 0
	v_mfma_f32_16x16x32_bf16 v[42:45], v[42:45], v[2:5], v[54:57]
	s_nop 2
	v_add_f32_e32 v54, v94, v93
	v_add_f32_e32 v54, v86, v54
	v_add_f32_e32 v54, v87, v54
	v_mfma_f32_16x16x32_bf16 v[38:41], v[38:41], v[2:5], v[50:53]
	s_nop 2
	v_add_f32_e32 v50, v82, v54
	v_add_f32_e32 v50, v78, v50
	v_add_f32_e32 v50, v79, v50
	v_mfma_f32_16x16x32_bf16 v[30:33], v[30:33], v[2:5], v[46:49]
	s_nop 2
	v_add_f32_e32 v46, v58, v50
	v_add_f32_e32 v46, v59, v46
	v_add_f32_e32 v46, v60, v46
	v_mfma_f32_16x16x32_bf16 v[2:5], v[26:29], v[2:5], v[34:37]
	v_add_f32_e32 v26, v61, v46
	v_add_f32_e32 v26, v62, v26
	v_add_f32_e32 v26, v63, v26
	ds_bpermute_b32 v0, v0, v26
	v_mfma_f32_16x16x32_bf16 v[22:25], v[22:25], v[6:9], v[42:45]
	s_waitcnt lgkmcnt(0)
	v_add_f32_e32 v0, v26, v0
	ds_bpermute_b32 v26, v212, v0
	v_mfma_f32_16x16x32_bf16 v[18:21], v[18:21], v[6:9], v[38:41]
	s_waitcnt lgkmcnt(0)
	v_add_f32_e32 v0, v0, v26
	v_div_scale_f32 v26, s[10:11], v0, v0, 1.0
	v_rcp_f32_e32 v27, v26
	v_mfma_f32_16x16x32_bf16 v[14:17], v[14:17], v[6:9], v[30:33]
	v_mfma_f32_16x16x32_bf16 v[2:5], v[10:13], v[6:9], v[2:5]
	v_fma_f32 v6, -v26, v27, 1.0
	v_fmac_f32_e32 v27, v6, v27
	v_div_scale_f32 v6, vcc, 1.0, v0, 1.0
	v_mul_f32_e32 v7, v6, v27
	v_fma_f32 v8, -v26, v7, v6
	v_fmac_f32_e32 v7, v8, v27
	v_fma_f32 v6, -v26, v7, v6
	v_div_fmas_f32 v6, v6, v27, v7
	v_div_fixup_f32 v0, v6, v0, 1.0
	v_mul_f32_e32 v6, v0, v22
	v_mul_f32_e32 v7, v0, v23
	v_cvt_pk_bf16_f32 v6, v6, v7
	v_mul_f32_e32 v7, v0, v24
	v_mul_f32_e32 v8, v0, v25
	v_cvt_pk_bf16_f32 v7, v7, v8
	ds_write_b64 v211, v[6:7]
	v_mul_f32_e32 v6, v0, v18
	v_mul_f32_e32 v7, v0, v19
	v_cvt_pk_bf16_f32 v6, v6, v7
	v_mul_f32_e32 v7, v0, v20
	v_mul_f32_e32 v8, v0, v21
	v_cvt_pk_bf16_f32 v7, v7, v8
	ds_write_b64 v211, v[6:7] offset:32
	v_mul_f32_e32 v6, v0, v14
	v_mul_f32_e32 v7, v0, v15
	v_cvt_pk_bf16_f32 v6, v6, v7
	v_mul_f32_e32 v7, v0, v16
	v_mul_f32_e32 v2, v0, v2
	v_mul_f32_e32 v3, v0, v3
	v_mul_f32_e32 v8, v0, v17
	v_cvt_pk_bf16_f32 v7, v7, v8
	ds_write_b64 v211, v[6:7] offset:64
	v_cvt_pk_bf16_f32 v2, v2, v3
	v_mul_f32_e32 v3, v0, v4
	v_mul_f32_e32 v0, v0, v5
	v_cvt_pk_bf16_f32 v3, v3, v0
	ds_write_b64 v211, v[2:3] offset:96
	v_mov_b32_e32 v11, s9
	v_or_b32_e32 v10, s8, v164
	ds_read_b128 v[2:5], v209
	ds_read_b128 v[6:9], v209 offset:1152
	v_lshlrev_b64 v[10:11], 11, v[10:11]
	v_lshl_add_u64 v[10:11], s[44:45], 0, v[10:11]
	v_lshl_add_u64 v[10:11], v[10:11], 0, s[26:27]
	v_lshl_add_u64 v[10:11], v[10:11], 0, v[166:167]
	s_waitcnt lgkmcnt(1)
	global_store_dwordx4 v[10:11], v[2:5], off
	s_nop 1
	v_add_co_u32_e32 v2, vcc, 0x4000, v10
	s_nop 1
	v_addc_co_u32_e32 v3, vcc, 0, v11, vcc
	s_waitcnt lgkmcnt(0)
	global_store_dwordx4 v[2:3], v[6:9], off
	s_waitcnt lgkmcnt(0)
	s_cbranch_scc0 .LBB0_372

; __global__ void __launch_bounds__(NTHR, 2) fwd_megakernel(Args kargs) {
	.amdhsa_kernel _Z14fwd_megakernel4Args
		.amdhsa_group_segment_fixed_size 0
		.amdhsa_private_segment_fixed_size 0
		.amdhsa_kernarg_size 456
		.amdhsa_user_sgpr_count 2
		.amdhsa_user_sgpr_dispatch_ptr 0
		.amdhsa_user_sgpr_queue_ptr 0
		.amdhsa_user_sgpr_kernarg_segment_ptr 1
		.amdhsa_user_sgpr_dispatch_id 0
		.amdhsa_user_sgpr_kernarg_preload_length 0
		.amdhsa_user_sgpr_kernarg_preload_offset 0
		.amdhsa_user_sgpr_private_segment_size 0
		.amdhsa_uses_dynamic_stack 0
		.amdhsa_enable_private_segment 0
		.amdhsa_system_sgpr_workgroup_id_x 1
		.amdhsa_system_sgpr_workgroup_id_y 0
		.amdhsa_system_sgpr_workgroup_id_z 0
		.amdhsa_system_sgpr_workgroup_info 0
		.amdhsa_system_vgpr_workitem_id 2
		.amdhsa_next_free_vgpr 256
		.amdhsa_next_free_sgpr 102
		.amdhsa_accum_offset 256
		.amdhsa_reserve_vcc 1
		.amdhsa_float_round_mode_32 0
		.amdhsa_float_round_mode_16_64 0
		.amdhsa_float_denorm_mode_32 3
		.amdhsa_float_denorm_mode_16_64 3
		.amdhsa_dx10_clamp 1
		.amdhsa_ieee_mode 1
		.amdhsa_fp16_overflow 0
		.amdhsa_tg_split 0
		.amdhsa_exception_fp_ieee_invalid_op 0
		.amdhsa_exception_fp_denorm_src 0
		.amdhsa_exception_fp_ieee_div_zero 0
		.amdhsa_exception_fp_ieee_overflow 0
		.amdhsa_exception_fp_ieee_underflow 0
		.amdhsa_exception_fp_ieee_inexact 0
		.amdhsa_exception_int_div_zero 0
	.end_amdhsa_kernel

; __global__ void __launch_bounds__(NTHR, 2) fwd_megakernel(Args kargs) {
amdhsa.kernels:
  - .agpr_count:     0
    .args:
      - .offset:         0
        .size:           200
        .value_kind:     by_value
      - .offset:         200
        .size:           4
        .value_kind:     hidden_block_count_x
      - .offset:         204
        .size:           4
        .value_kind:     hidden_block_count_y
      - .offset:         208
        .size:           4
        .value_kind:     hidden_block_count_z
      - .offset:         212
        .size:           2
        .value_kind:     hidden_group_size_x
      - .offset:         214
        .size:           2
        .value_kind:     hidden_group_size_y
      - .offset:         216
        .size:           2
        .value_kind:     hidden_group_size_z
      - .offset:         218
        .size:           2
        .value_kind:     hidden_remainder_x
      - .offset:         220
        .size:           2
        .value_kind:     hidden_remainder_y
      - .offset:         222
        .size:           2
        .value_kind:     hidden_remainder_z
      - .offset:         240
        .size:           8
        .value_kind:     hidden_global_offset_x
      - .offset:         248
        .size:           8
        .value_kind:     hidden_global_offset_y
      - .offset:         256
        .size:           8
        .value_kind:     hidden_global_offset_z
      - .offset:         264
        .size:           2
        .value_kind:     hidden_grid_dims
      - .offset:         288
        .size:           8
        .value_kind:     hidden_multigrid_sync_arg
      - .offset:         320
        .size:           4
        .value_kind:     hidden_dynamic_lds_size
    .group_segment_fixed_size: 0
    .kernarg_segment_align: 8
    .kernarg_segment_size: 456
    .language:       OpenCL C
    .language_version:
      - 2
      - 0
    .max_flat_workgroup_size: 512
    .name:           _Z14fwd_megakernel4Args
    .private_segment_fixed_size: 0
    .sgpr_count:     108
    .sgpr_spill_count: 174
    .symbol:         _Z14fwd_megakernel4Args.kd
    .uniform_work_group_size: 1
    .uses_dynamic_stack: false
    .vgpr_count:     256
    .vgpr_spill_count: 0
    .wavefront_size: 64
